# v16 + lru_job scan loop with batched LDS reads + la_job/gla_job intra-chunk stage straightened with hoisted LDS reads
# baseline (speedup 1.0000x reference)
.LBB0_839:
	s_nop 7
	v_cndmask_b32_e64 v1, v66, 0, s[54:55]
	v_cndmask_b32_e64 v35, v67, 0, s[56:57]
	v_cndmask_b32_e64 v37, v68, 0, s[58:59]
	v_cndmask_b32_e64 v67, v69, 0, s[60:61]
	v_cvt_pk_bf16_f32 v66, v1, v35
	v_cvt_pk_bf16_f32 v67, v37, v67
	ds_write_b64 v161, v[66:67]
	ds_read_b128 v[184:187], v132
	ds_read_b128 v[188:191], v135
	v_add_u32_e32 v1, 0x1000, v162
	ds_read_b64 v[192:193], v1 offset:256
	ds_read_b64 v[194:195], v1 offset:288
	ds_read_b64 v[196:197], v162
	ds_read_b64 v[198:199], v162 offset:32
	v_add_u32_e32 v35, 0x2000, v162
	ds_read_b64 v[200:201], v35 offset:512
	ds_read_b64 v[202:203], v35 offset:544
	v_add_u32_e32 v37, 0x3000, v162
	ds_read_b64 v[204:205], v37 offset:768
	ds_read_b64 v[206:207], v37 offset:800
	s_waitcnt lgkmcnt(11)
	s_waitcnt lgkmcnt(9)
	v_pk_mul_f32 v[68:69], v[4:5], v[186:187]
	ds_read_b128 v[208:211], v136
	v_pk_mul_f32 v[66:67], v[2:3], v[184:185]
	s_waitcnt lgkmcnt(9)
	v_pk_mul_f32 v[72:73], v[12:13], v[190:191]
	ds_read_b128 v[184:187], v137
	v_cvt_pk_bf16_f32 v66, v66, v67
	v_cvt_pk_bf16_f32 v67, v68, v69
	v_pk_mul_f32 v[68:69], v[10:11], v[188:189]
	v_cvt_pk_bf16_f32 v68, v68, v69
	v_cvt_pk_bf16_f32 v69, v72, v73
	s_nop 0
	s_waitcnt lgkmcnt(6)
	v_mfma_f32_16x16x32_bf16 v[70:73], v[66:69], v[196:199], 0
	s_sub_i32 s5, s8, 64
	s_add_u32 s18, s5, s72
	s_addc_u32 s19, 0, s74
	v_mfma_f32_16x16x32_bf16 v[74:77], v[66:69], v[192:195], 0
	ds_read_b64 v[188:189], v162 offset:64
	ds_read_b64 v[190:191], v162 offset:96
	ds_read_b64 v[192:193], v1 offset:320
	ds_read_b64 v[194:195], v1 offset:352
	v_mov_b32_e32 v36, 0
	v_cmp_gt_i32_e64 s[68:69], s9, v95
	v_or_b32_e32 v116, s18, v95
	s_waitcnt lgkmcnt(8)
	v_mfma_f32_16x16x32_bf16 v[78:81], v[66:69], v[200:203], 0
	ds_read_b64 v[196:197], v35 offset:576
	ds_read_b64 v[198:199], v35 offset:608
	s_waitcnt lgkmcnt(8)
	v_mfma_f32_16x16x32_bf16 v[66:69], v[66:69], v[204:207], 0
	ds_read_b64 v[200:201], v37 offset:832
	ds_read_b64 v[202:203], v37 offset:864
	s_waitcnt lgkmcnt(9)
	v_pk_mul_f32 v[106:107], v[8:9], v[210:211]
	ds_read_b128 v[204:207], v138
	v_pk_mul_f32 v[104:105], v[6:7], v[208:209]
	s_waitcnt lgkmcnt(9)
	v_pk_mul_f32 v[110:111], v[16:17], v[186:187]
	ds_read_b128 v[208:211], v139
	v_cvt_pk_bf16_f32 v104, v104, v105
	v_cvt_pk_bf16_f32 v105, v106, v107
	v_pk_mul_f32 v[106:107], v[14:15], v[184:185]
	s_nop 0
	v_cvt_pk_bf16_f32 v106, v106, v107
	v_cvt_pk_bf16_f32 v107, v110, v111
	s_nop 0
	s_waitcnt lgkmcnt(8)
	v_mfma_f32_16x16x32_bf16 v[70:73], v[104:107], v[188:191], v[70:73]
	ds_read_b64 v[184:185], v162 offset:128
	ds_read_b64 v[186:187], v162 offset:160
	s_waitcnt lgkmcnt(8)
	v_mfma_f32_16x16x32_bf16 v[74:77], v[104:107], v[192:195], v[74:77]
	ds_read_b64 v[188:189], v1 offset:384
	ds_read_b64 v[190:191], v1 offset:416
	s_waitcnt lgkmcnt(8)
	v_mfma_f32_16x16x32_bf16 v[78:81], v[104:107], v[196:199], v[78:81]
	ds_read_b64 v[192:193], v35 offset:640
	ds_read_b64 v[194:195], v35 offset:672
	s_waitcnt lgkmcnt(8)
	v_mfma_f32_16x16x32_bf16 v[66:69], v[104:107], v[200:203], v[66:69]
	ds_read_b64 v[196:197], v37 offset:896
	ds_read_b64 v[198:199], v37 offset:928
	s_waitcnt lgkmcnt(9)
	v_pk_mul_f32 v[106:107], v[20:21], v[206:207]
	ds_read_b128 v[200:203], v140
	v_pk_mul_f32 v[104:105], v[18:19], v[204:205]
	s_waitcnt lgkmcnt(9)
	v_pk_mul_f32 v[110:111], v[24:25], v[210:211]
	ds_read_b128 v[204:207], v141
	v_cvt_pk_bf16_f32 v104, v104, v105
	v_cvt_pk_bf16_f32 v105, v106, v107
	v_pk_mul_f32 v[106:107], v[22:23], v[208:209]
	s_nop 0
	v_cvt_pk_bf16_f32 v106, v106, v107
	v_cvt_pk_bf16_f32 v107, v110, v111
	s_nop 0
	s_waitcnt lgkmcnt(8)
	v_mfma_f32_16x16x32_bf16 v[70:73], v[104:107], v[184:187], v[70:73]
	ds_read_b64 v[184:185], v162 offset:192
	ds_read_b64 v[186:187], v162 offset:224
	s_waitcnt lgkmcnt(8)
	v_mfma_f32_16x16x32_bf16 v[74:77], v[104:107], v[188:191], v[74:77]
	ds_read_b64 v[188:189], v1 offset:448
	ds_read_b64 v[190:191], v1 offset:480
	s_waitcnt lgkmcnt(8)
	v_mfma_f32_16x16x32_bf16 v[78:81], v[104:107], v[192:195], v[78:81]
	ds_read_b64 v[192:193], v35 offset:704
	ds_read_b64 v[194:195], v35 offset:736
	s_waitcnt lgkmcnt(8)
	v_mfma_f32_16x16x32_bf16 v[66:69], v[104:107], v[196:199], v[66:69]
	s_waitcnt lgkmcnt(7)
	v_pk_mul_f32 v[106:107], v[28:29], v[202:203]
	v_pk_mul_f32 v[104:105], v[26:27], v[200:201]
	s_waitcnt lgkmcnt(6)
	v_pk_mul_f32 v[110:111], v[32:33], v[206:207]
	v_cvt_pk_bf16_f32 v104, v104, v105
	v_cvt_pk_bf16_f32 v105, v106, v107
	v_pk_mul_f32 v[106:107], v[30:31], v[204:205]
	s_nop 0
	v_cvt_pk_bf16_f32 v106, v106, v107
	v_cvt_pk_bf16_f32 v107, v110, v111
	s_nop 0
	s_waitcnt lgkmcnt(4)
	v_mfma_f32_16x16x32_bf16 v[108:111], v[104:107], v[184:187], v[70:73]
	s_nop 2
	s_waitcnt lgkmcnt(2)
	v_mfma_f32_16x16x32_bf16 v[74:77], v[104:107], v[188:191], v[74:77]
	s_waitcnt lgkmcnt(0)
	v_mfma_f32_16x16x32_bf16 v[70:73], v[104:107], v[192:195], v[78:81]
	s_nop 2
	ds_read_b64 v[78:79], v37 offset:960
	ds_read_b64 v[80:81], v37 offset:992
	s_waitcnt lgkmcnt(0)
	v_mfma_f32_16x16x32_bf16 v[66:69], v[104:107], v[78:81], v[66:69]
	s_barrier
	ds_read_b128 v[184:187], v174
	ds_read_b128 v[188:191], v174 offset:64
	ds_read_b128 v[192:195], v174 offset:2304
	ds_read_b128 v[196:199], v174 offset:2368
	ds_read_b128 v[200:203], v174 offset:4608
	ds_read_b128 v[204:207], v174 offset:4672
	s_waitcnt lgkmcnt(6)
	s_waitcnt lgkmcnt(5)
	v_mfma_f32_16x16x32_bf16 v[78:81], v[62:65], v[184:187], v[108:111]
	ds_read_b128 v[184:187], v174 offset:6912
	v_mov_b32_e32 v37, 0
	s_waitcnt lgkmcnt(5)
	v_mfma_f32_16x16x32_bf16 v[78:81], v[58:61], v[188:191], v[78:81]
	ds_read_b128 v[188:191], v174 offset:6976
	s_and_saveexec_b64 s[20:21], s[68:69]
	s_nop 0
	v_mov_b32_e32 v117, s19
	v_lshlrev_b64 v[36:37], 12, v[116:117]
	v_lshl_add_u64 v[36:37], v[102:103], 0, v[36:37]
	global_load_dwordx2 v[36:37], v[36:37], off
	s_or_b64 exec, exec, s[20:21]
	v_and_b32_e32 v35, 64, v229
	v_xor_b32_e32 v1, 16, v229
	v_add_u32_e32 v90, 64, v35
	v_cmp_lt_i32_e32 vcc, v1, v90
	s_nop 0
	v_mul_f32_e32 v104, v81, v81
	v_fmac_f32_e32 v104, v80, v80
	v_cndmask_b32_e32 v1, v229, v1, vcc
	v_lshlrev_b32_e32 v35, 2, v1
	v_mul_f32_e32 v1, v79, v79
	v_fmac_f32_e32 v1, v78, v78
	v_add_f32_e32 v1, v1, v104
	ds_bpermute_b32 v104, v35, v1
	v_xor_b32_e32 v105, 32, v229
	v_cmp_lt_i32_e32 vcc, v105, v90
	s_waitcnt lgkmcnt(0)
	v_add_f32_e32 v104, v1, v104
	v_cndmask_b32_e32 v90, v229, v105, vcc
	v_lshlrev_b32_e32 v90, 2, v90
	ds_bpermute_b32 v105, v90, v104
	s_and_saveexec_b64 s[20:21], s[36:37]
	s_nop 0
	s_waitcnt lgkmcnt(0)
	v_add_f32_e32 v1, v104, v105
	v_add_u32_e32 v104, s95, v142
	ds_write_b32 v104, v1
	s_or_b64 exec, exec, s[20:21]
	s_min_i32 s5, s9, 64
	v_cmp_gt_i32_e64 s[66:67], s5, v94
	v_mov_b32_e32 v114, 0
	v_or_b32_e32 v112, s18, v94
	v_mfma_f32_16x16x32_bf16 v[74:77], v[62:65], v[192:195], v[74:77]
	v_mov_b32_e32 v115, 0
	v_mfma_f32_16x16x32_bf16 v[74:77], v[58:61], v[196:199], v[74:77]
	s_and_saveexec_b64 s[20:21], s[66:67]
	s_nop 0
	v_mov_b32_e32 v113, s19
	v_lshlrev_b64 v[104:105], 12, v[112:113]
	v_lshl_add_u64 v[104:105], v[102:103], 0, v[104:105]
	global_load_dwordx2 v[114:115], v[104:105], off
	s_or_b64 exec, exec, s[20:21]
	s_nop 4
	v_mul_f32_e32 v1, v75, v75
	v_mul_f32_e32 v104, v77, v77
	v_fmac_f32_e32 v1, v74, v74
	v_fmac_f32_e32 v104, v76, v76
	v_add_f32_e32 v1, v1, v104
	ds_bpermute_b32 v104, v35, v1
	s_waitcnt lgkmcnt(0)
	v_add_f32_e32 v104, v1, v104
	ds_bpermute_b32 v105, v90, v104
	s_and_saveexec_b64 s[20:21], s[36:37]
	s_nop 0
	s_waitcnt lgkmcnt(0)
	v_add_f32_e32 v1, v104, v105
	v_add_u32_e32 v104, s95, v143
	ds_write_b32 v104, v1
	s_or_b64 exec, exec, s[20:21]
	v_cmp_gt_i32_e64 s[64:65], s5, v96
	v_mov_b32_e32 v110, 0
	v_lshl_add_u64 v[108:109], s[18:19], 0, v[96:97]
	v_mov_b32_e32 v111, 0
	v_mfma_f32_16x16x32_bf16 v[70:73], v[62:65], v[200:203], v[70:73]
	v_mfma_f32_16x16x32_bf16 v[70:73], v[58:61], v[204:207], v[70:73]
	s_and_saveexec_b64 s[20:21], s[64:65]
	s_nop 0
	v_lshlrev_b64 v[104:105], 12, v[108:109]
	v_lshl_add_u64 v[104:105], v[102:103], 0, v[104:105]
	global_load_dwordx2 v[110:111], v[104:105], off
	s_or_b64 exec, exec, s[20:21]
	s_nop 4
	v_mul_f32_e32 v1, v71, v71
	v_mul_f32_e32 v104, v73, v73
	v_fmac_f32_e32 v1, v70, v70
	v_fmac_f32_e32 v104, v72, v72
	v_add_f32_e32 v1, v1, v104
	ds_bpermute_b32 v104, v35, v1
	s_waitcnt lgkmcnt(0)
	v_add_f32_e32 v104, v1, v104
	ds_bpermute_b32 v105, v90, v104
	s_and_saveexec_b64 s[20:21], s[36:37]
	s_nop 0
	s_waitcnt lgkmcnt(0)
	v_add_f32_e32 v1, v104, v105
	v_add_u32_e32 v104, s95, v145
	ds_write_b32 v104, v1
	s_or_b64 exec, exec, s[20:21]
	v_cmp_gt_i32_e64 s[62:63], s5, v98
	v_mfma_f32_16x16x32_bf16 v[66:69], v[62:65], v[184:187], v[66:69]
	v_mfma_f32_16x16x32_bf16 v[66:69], v[58:61], v[188:191], v[66:69]
	v_mov_b32_e32 v106, 0
	v_lshl_add_u64 v[104:105], s[18:19], 0, v[98:99]
	v_mov_b32_e32 v107, 0
	s_and_saveexec_b64 s[20:21], s[62:63]
	s_nop 0
	v_lshlrev_b64 v[106:107], 12, v[104:105]
	v_lshl_add_u64 v[106:107], v[102:103], 0, v[106:107]
	global_load_dwordx2 v[106:107], v[106:107], off
	s_or_b64 exec, exec, s[20:21]
	s_nop 1
	v_mul_f32_e32 v1, v67, v67
	v_mul_f32_e32 v113, v69, v69
	v_fmac_f32_e32 v1, v66, v66
	v_fmac_f32_e32 v113, v68, v68
	v_add_f32_e32 v1, v1, v113
	ds_bpermute_b32 v35, v35, v1
	s_waitcnt lgkmcnt(0)
	v_add_f32_e32 v35, v1, v35
	ds_bpermute_b32 v90, v90, v35
	s_and_saveexec_b64 s[20:21], s[36:37]
	s_nop 0
	s_waitcnt lgkmcnt(0)
	v_add_f32_e32 v1, v35, v90
	v_add_u32_e32 v35, s95, v146
	ds_write_b32 v35, v1
	s_or_b64 exec, exec, s[20:21]
